# speedup vs baseline: 1.0194x; 1.0000x over previous
.LBB0_1073:
	s_mov_b32 s42, 32
	s_and_b64 vcc, exec, s[0:1]
	s_cbranch_vccz .LBB0_1075
	s_cmpk_gt_u32 s33, 0x7d7
	s_cselect_b32 s0, 24, 0
	s_cmp_lg_u32 s87, 0
	s_cselect_b32 s0, s0, 0
	s_add_i32 s0, s33, s0
	s_add_i32 s0, s0, -16
	s_mul_hi_u32 s1, s0, 0x38e38e39
	s_lshr_b32 s1, s1, 6
	s_lshl_b32 s2, s1, 2
	s_sub_i32 s3, 32, s2
	s_min_u32 s3, s3, 4
	s_mulk_i32 s1, 0x120
	s_sub_i32 s4, s0, s1
	v_cvt_f32_ubyte0_e32 v1, s3
	v_cvt_f32_u32_e32 v0, s4
	v_rcp_iflag_f32_e32 v2, v1
	s_nop 0
	v_mul_f32_e32 v2, v0, v2
	v_trunc_f32_e32 v2, v2
	v_cvt_u32_f32_e32 v3, v2
	v_fma_f32 v0, -v2, v1, v0
	v_cmp_ge_f32_e64 s[0:1], |v0|, v1
	s_cmp_lg_u64 s[0:1], 0
	v_readfirstlane_b32 s0, v3
	s_addc_u32 s0, s0, 0
	s_mul_i32 s1, s0, s3
	s_sub_i32 s1, s4, s1
	s_and_b32 s1, s1, 0xffff
	s_add_i32 s42, s2, s1
	s_and_b32 s18, s0, 0xffff

.LBB0_1415:
	s_andn2_b64 vcc, exec, s[0:1]
	s_cbranch_vccnz .LBB0_1687
	s_add_i32 s0, s79, 0x8a8
	s_cmp_lt_u32 s79, 24
	s_cselect_b32 s1, 0xe0, 0
	s_sub_i32 s0, s0, s1
	s_mul_hi_i32 s1, s0, 0x38e38e39
	s_lshr_b32 s2, s1, 31
	s_ashr_i32 s1, s1, 6
	s_add_i32 s1, s1, s2
	s_lshl_b32 s33, s1, 2
	s_mulk_i32 s1, 0x120
	s_sub_i32 s26, s0, s1
	s_bfe_u32 s0, s26, 0x2001d
	s_add_i32 s0, s26, s0
	s_sext_i32_i16 s1, s0
	s_and_b32 s0, s0, 0xfffc
	s_sub_i32 s0, s26, s0
	s_sext_i32_i16 s0, s0
	s_add_i32 s33, s33, s0
	v_mov_b32_e32 v128, v244
	s_lshr_b32 s24, s1, 2
	s_lshl_b32 s0, s33, 8
	s_mov_b32 s1, 0x7fff0
	v_lshrrev_b32_e32 v1, 3, v128
	v_bfe_u32 v2, v128, 2, 4
	v_and_or_b32 v1, v1, s1, v2
	s_ashr_i32 s1, s0, 31
	s_lshl_b32 s20, s24, 8
	s_lshl_b64 s[2:3], s[0:1], 13
	s_add_u32 s4, s82, s2
	s_addc_u32 s1, s83, s3
	s_ashr_i32 s21, s20, 31
	s_lshl_b64 s[2:3], s[20:21], 13
	v_readlane_b32 s6, v249, 24
	v_lshlrev_b32_e32 v135, 4, v128
	v_readlane_b32 s7, v249, 25
	s_add_u32 s8, s6, s2
	v_and_b32_e32 v0, 32, v128
	s_addc_u32 s2, s7, s3
	v_add_u32_e32 v140, 0x10000, v135
	v_and_b32_e32 v2, 64, v128
	v_bitop3_b32 v0, v135, v0, 48 bitop3:0x6c
	v_lshlrev_b32_e32 v1, 13, v1
	s_and_b32 s5, s1, 0xffff
	s_mov_b32 s7, 0x20000
	s_brev_b32 s6, -2
	s_and_b32 s9, s2, 0xffff
	v_readfirstlane_b32 s1, v140
	v_add_u32_e32 v141, 0x12000, v135
	v_or3_b32 v130, v2, v0, v1
	s_mov_b32 s12, s8
	s_mov_b32 s13, s9
	s_mov_b32 s14, s6
	s_mov_b32 s15, s7
	s_mov_b32 m0, s1
	v_readfirstlane_b32 s2, v141
	buffer_load_dwordx4 v130, s[12:15], 0 offen lds
	s_mov_b32 s1, 0x80000
	s_mov_b32 m0, s2
	v_readfirstlane_b32 s2, v135
	v_add_u32_e32 v142, 0x2000, v135
	buffer_load_dwordx4 v130, s[12:15], s1 offen lds
	s_mov_b32 m0, s2
	v_readfirstlane_b32 s2, v142
	v_add_u32_e32 v143, 0x14000, v135
	buffer_load_dwordx4 v130, s[4:7], 0 offen lds
	s_mov_b32 m0, s2
	v_readfirstlane_b32 s2, v143
	v_add_u32_e32 v144, 0x16000, v135
	buffer_load_dwordx4 v130, s[4:7], s1 offen lds
	s_mov_b32 s1, 0x100000
	s_mov_b32 m0, s2
	v_readfirstlane_b32 s3, v144
	v_add_u32_e32 v145, 0x4000, v135
	buffer_load_dwordx4 v130, s[12:15], s1 offen lds
	s_mov_b32 s2, 0x180000
	s_mov_b32 m0, s3
	v_readfirstlane_b32 s3, v145
	buffer_load_dwordx4 v130, s[12:15], s2 offen lds
	s_mov_b32 m0, s3
	v_add_u32_e32 v146, 0x6000, v135
	buffer_load_dwordx4 v130, s[4:7], s1 offen lds
	v_readfirstlane_b32 s1, v146
	s_mov_b32 m0, s1
	v_ashrrev_i32_e32 v0, 8, v128
	buffer_load_dwordx4 v130, s[4:7], s2 offen lds
	s_mov_b32 s10, s6
	s_mov_b32 s11, s7
	v_cmp_eq_u32_e32 vcc, 1, v0
	s_and_saveexec_b64 s[2:3], vcc
	s_cbranch_execz .LBB0_1418
	s_barrier
